# sample GEMM (s4/s6): K-step fragment reads batched with counted lgkmcnt + 3-deep global prefetch
# baseline (speedup 1.0000x reference)
.LBB0_232:
	v_lshl_add_u32 v36, v45, 1, s23
	v_lshl_add_u32 v50, v43, 1, v36
	v_lshl_add_u32 v36, v44, 1, v36
	ds_read_b128 v[96:99], v50 offset:34816
	ds_read_b128 v[112:115], v36
	ds_read_b128 v[128:131], v36 offset:4352
	ds_read_b128 v[100:103], v50 offset:34880
	ds_read_b128 v[116:119], v36 offset:64
	ds_read_b128 v[132:135], v36 offset:4416
	ds_read_b128 v[104:107], v50 offset:34944
	ds_read_b128 v[120:123], v36 offset:128
	ds_read_b128 v[136:139], v36 offset:4480
	ds_read_b128 v[108:111], v50 offset:35008
	ds_read_b128 v[124:127], v36 offset:192
	ds_read_b128 v[54:57], v36 offset:4544
	s_add_i32 s1, s1, 64
	v_lshl_add_u64 v[32:33], v[32:33], 0, s[68:69]
	v_lshl_add_u64 v[34:35], v[34:35], 0, s[68:69]
	s_cmp_eq_u32 s4, s19
	s_waitcnt lgkmcnt(10)
	v_mfma_f32_16x16x32_bf16 v[22:25], v[96:99], v[112:115], v[22:25]
	s_waitcnt lgkmcnt(9)
	v_mfma_f32_16x16x32_bf16 v[2:5], v[96:99], v[128:131], v[2:5]
	s_waitcnt lgkmcnt(7)
	v_mfma_f32_16x16x32_bf16 v[22:25], v[100:103], v[116:119], v[22:25]
	s_waitcnt lgkmcnt(6)
	v_mfma_f32_16x16x32_bf16 v[2:5], v[100:103], v[132:135], v[2:5]
	s_waitcnt lgkmcnt(4)
	v_mfma_f32_16x16x32_bf16 v[22:25], v[104:107], v[120:123], v[22:25]
	s_waitcnt lgkmcnt(3)
	v_mfma_f32_16x16x32_bf16 v[2:5], v[104:107], v[136:139], v[2:5]
	s_waitcnt lgkmcnt(1)
	v_mfma_f32_16x16x32_bf16 v[22:25], v[108:111], v[124:127], v[22:25]
	s_waitcnt lgkmcnt(0)
	v_mfma_f32_16x16x32_bf16 v[2:5], v[108:111], v[54:57], v[2:5]
	s_cbranch_scc1 .LBB0_234
	s_mov_b32 s8, s19
	s_branch .LBB0_228
